# v12: v5 + deferred (threshold 8) running-max update in the sparse-softmax attention
# speedup vs baseline: 1.0049x; 1.0049x over previous
.LBB0_67:
	s_mul_i32 s0, s49, 0x8c00
	s_add_i32 s47, s0, 0
	v_add3_u32 v217, s47, v209, v210
	v_lshrrev_b32_e32 v218, v186, v202
	v_lshrrev_b32_e32 v203, v186, v203
	s_and_saveexec_b64 s[0:1], s[6:7]
	s_xor_b64 s[0:1], exec, s[0:1]
	s_cbranch_execz .LBB0_71
	v_not_b32_e32 v66, v218
	v_not_b32_e32 v82, v203
	v_bfe_i32 v83, v66, 0, 1
	v_bfe_i32 v174, v82, 0, 1
	v_bfe_i32 v67, v66, 1, 1
	v_bfe_i32 v175, v82, 1, 1
	v_bfe_i32 v68, v66, 2, 1
	v_bfe_i32 v84, v82, 2, 1
	v_bfe_i32 v69, v66, 3, 1
	v_bfe_i32 v85, v82, 3, 1
	v_bfe_i32 v70, v66, 8, 1
	v_bfe_i32 v86, v82, 8, 1
	v_bfe_i32 v71, v66, 9, 1
	v_bfe_i32 v87, v82, 9, 1
	v_bfe_i32 v72, v66, 10, 1
	v_bfe_i32 v88, v82, 10, 1
	v_bfe_i32 v73, v66, 11, 1
	v_bfe_i32 v89, v82, 11, 1
	v_bfe_i32 v74, v66, 16, 1
	v_bfe_i32 v90, v82, 16, 1
	v_bfe_i32 v75, v66, 17, 1
	v_bfe_i32 v91, v82, 17, 1
	v_bfe_i32 v76, v66, 18, 1
	v_bfe_i32 v92, v82, 18, 1
	v_bfe_i32 v77, v66, 19, 1
	v_bfe_i32 v93, v82, 19, 1
	v_bfe_i32 v78, v66, 24, 1
	v_bfe_i32 v94, v82, 24, 1
	v_bfe_i32 v79, v66, 25, 1
	v_bfe_i32 v95, v82, 25, 1
	v_bfe_i32 v80, v66, 26, 1
	v_bfe_i32 v96, v82, 26, 1
	v_bfe_i32 v66, v66, 27, 1
	v_bfe_i32 v82, v82, 27, 1
	s_nop 0
	v_and_b32_e32 v79, 0xff800000, v79
	v_and_b32_e32 v81, 0xff800000, v66
	v_and_b32_e32 v66, 0xff800000, v83
	v_and_b32_e32 v97, 0xff800000, v82
	v_and_b32_e32 v83, 0xff800000, v175
	v_and_b32_e32 v82, 0xff800000, v174
	ds_read_b128 v[218:221], v217 offset:8704
	ds_read_b128 v[222:225], v217
	ds_read_b128 v[226:229], v217 offset:32
	ds_read_b128 v[232:235], v217 offset:8736
	ds_read_b128 v[236:239], v217 offset:64
	ds_read_b128 v[248:251], v217 offset:8768
	ds_read_b128 v[240:243], v217 offset:96
	ds_read_b128 v[174:177], v217 offset:8800
	v_and_b32_e32 v80, 0xff800000, v80
	v_and_b32_e32 v78, 0xff800000, v78
	v_and_b32_e32 v77, 0xff800000, v77
	v_and_b32_e32 v76, 0xff800000, v76
	v_and_b32_e32 v75, 0xff800000, v75
	v_and_b32_e32 v74, 0xff800000, v74
	v_and_b32_e32 v73, 0xff800000, v73
	v_and_b32_e32 v72, 0xff800000, v72
	v_and_b32_e32 v71, 0xff800000, v71
	v_and_b32_e32 v70, 0xff800000, v70
	v_and_b32_e32 v69, 0xff800000, v69
	v_and_b32_e32 v68, 0xff800000, v68
	v_and_b32_e32 v67, 0xff800000, v67
	v_and_b32_e32 v96, 0xff800000, v96
	v_and_b32_e32 v95, 0xff800000, v95
	v_and_b32_e32 v94, 0xff800000, v94
	v_and_b32_e32 v93, 0xff800000, v93
	v_and_b32_e32 v92, 0xff800000, v92
	v_and_b32_e32 v91, 0xff800000, v91
	v_and_b32_e32 v90, 0xff800000, v90
	v_and_b32_e32 v89, 0xff800000, v89
	v_and_b32_e32 v88, 0xff800000, v88
	v_and_b32_e32 v87, 0xff800000, v87
	v_and_b32_e32 v86, 0xff800000, v86
	v_and_b32_e32 v85, 0xff800000, v85
	v_and_b32_e32 v84, 0xff800000, v84
	s_setprio 1
	s_waitcnt lgkmcnt(6)
	v_mfma_f32_32x32x16_bf16 v[66:81], v[222:225], v[98:101], v[66:81]
	v_mfma_f32_32x32x16_bf16 v[82:97], v[218:221], v[98:101], v[82:97]
	s_waitcnt lgkmcnt(5)
	v_mfma_f32_32x32x16_bf16 v[66:81], v[226:229], v[102:105], v[66:81]
	s_waitcnt lgkmcnt(4)
	v_mfma_f32_32x32x16_bf16 v[82:97], v[232:235], v[102:105], v[82:97]
	s_waitcnt lgkmcnt(3)
	v_mfma_f32_32x32x16_bf16 v[66:81], v[236:239], v[106:109], v[66:81]
	s_waitcnt lgkmcnt(2)
	v_mfma_f32_32x32x16_bf16 v[82:97], v[248:251], v[106:109], v[82:97]
	s_waitcnt lgkmcnt(1)
	v_mfma_f32_32x32x16_bf16 v[66:81], v[240:243], v[110:113], v[66:81]
	s_waitcnt lgkmcnt(0)
	v_mfma_f32_32x32x16_bf16 v[82:97], v[174:177], v[110:113], v[82:97]
	s_setprio 0
	ds_read_b128 v[174:177], v217 offset:128
	ds_read_b128 v[218:221], v217 offset:160
	ds_read_b128 v[222:225], v217 offset:8832
	ds_read_b128 v[226:229], v217 offset:8864
	ds_read_b128 v[232:235], v217 offset:192
	ds_read_b128 v[236:239], v217 offset:224
	ds_read_b128 v[240:243], v217 offset:8896
	ds_read_b128 v[248:251], v217 offset:8928
	s_setprio 1
	s_waitcnt lgkmcnt(7)
	v_mfma_f32_32x32x16_bf16 v[66:81], v[174:177], v[114:117], v[66:81]
	s_waitcnt lgkmcnt(5)
	v_mfma_f32_32x32x16_bf16 v[82:97], v[222:225], v[114:117], v[82:97]
	v_mfma_f32_32x32x16_bf16 v[66:81], v[218:221], v[118:121], v[66:81]
	s_waitcnt lgkmcnt(4)
	v_mfma_f32_32x32x16_bf16 v[82:97], v[226:229], v[118:121], v[82:97]
	s_waitcnt lgkmcnt(3)
	v_mfma_f32_32x32x16_bf16 v[66:81], v[232:235], v[122:125], v[66:81]
	s_waitcnt lgkmcnt(1)
	v_mfma_f32_32x32x16_bf16 v[82:97], v[240:243], v[122:125], v[82:97]
	v_mfma_f32_32x32x16_bf16 v[66:81], v[236:239], v[126:129], v[66:81]
	s_waitcnt lgkmcnt(0)
	v_mfma_f32_32x32x16_bf16 v[82:97], v[248:251], v[126:129], v[82:97]
	s_setprio 0
	v_max3_f32 v174, v231, v66, v82
	s_nop 0
	v_max3_f32 v174, v174, v67, v83
	s_nop 0
	v_max3_f32 v174, v174, v68, v84
	s_nop 0
	v_max3_f32 v174, v174, v69, v85
	s_nop 0
	v_max3_f32 v174, v174, v70, v86
	s_nop 0
	v_max3_f32 v174, v174, v71, v87
	s_nop 0
	v_max3_f32 v174, v174, v72, v88
	s_nop 0
	v_max3_f32 v174, v174, v73, v89
	s_nop 0
	v_max3_f32 v174, v174, v74, v90
	s_nop 0
	v_max3_f32 v174, v174, v75, v91
	s_nop 0
	v_max3_f32 v174, v174, v76, v92
	s_nop 0
	v_max3_f32 v174, v174, v77, v93
	s_nop 0
	v_max3_f32 v174, v174, v78, v94
	s_nop 0
	v_max3_f32 v174, v174, v79, v95
	s_nop 0
	v_max3_f32 v174, v174, v80, v96
	s_nop 0
	v_max3_f32 v174, v174, v81, v97
	s_nop 0
	v_mov_b32_e32 v175, v174
	s_nop 1
	v_permlane32_swap_b32_e32 v174, v175
	v_max_f32_e32 v174, v174, v175
	v_add_f32_e32 v175, 0x41000000, v195
	v_cmp_gt_f32_e32 vcc, v174, v175
	v_max_f32_e32 v174, v195, v174
	s_nop 0
	v_cndmask_b32_e32 v215, v195, v174, vcc
	v_cmp_neq_f32_e32 vcc, s59, v215
	s_nop 1
	v_cndmask_b32_e32 v203, 0, v215, vcc
	v_sub_f32_e32 v174, v195, v203
	v_exp_f32_e32 v202, v174
	s_nop 0
	v_cmp_eq_f32_e32 vcc, 1.0, v202
	s_cmp_eq_u64 vcc, exec
	s_cbranch_scc1 .LBB0_70
	v_pk_mul_f32 v[64:65], v[64:65], v[202:203] op_sel_hi:[1,0]
	v_pk_mul_f32 v[62:63], v[62:63], v[202:203] op_sel_hi:[1,0]
	v_pk_mul_f32 v[60:61], v[60:61], v[202:203] op_sel_hi:[1,0]
	v_pk_mul_f32 v[58:59], v[58:59], v[202:203] op_sel_hi:[1,0]
	v_pk_mul_f32 v[56:57], v[56:57], v[202:203] op_sel_hi:[1,0]
	v_pk_mul_f32 v[54:55], v[54:55], v[202:203] op_sel_hi:[1,0]
	v_pk_mul_f32 v[52:53], v[52:53], v[202:203] op_sel_hi:[1,0]
	v_pk_mul_f32 v[50:51], v[50:51], v[202:203] op_sel_hi:[1,0]
	v_pk_mul_f32 v[48:49], v[48:49], v[202:203] op_sel_hi:[1,0]
	v_pk_mul_f32 v[46:47], v[46:47], v[202:203] op_sel_hi:[1,0]
	v_pk_mul_f32 v[44:45], v[44:45], v[202:203] op_sel_hi:[1,0]
	v_pk_mul_f32 v[42:43], v[42:43], v[202:203] op_sel_hi:[1,0]
	v_pk_mul_f32 v[40:41], v[40:41], v[202:203] op_sel_hi:[1,0]
	v_pk_mul_f32 v[38:39], v[38:39], v[202:203] op_sel_hi:[1,0]
	v_pk_mul_f32 v[36:37], v[36:37], v[202:203] op_sel_hi:[1,0]
	v_pk_mul_f32 v[34:35], v[34:35], v[202:203] op_sel_hi:[1,0]
	v_pk_mul_f32 v[32:33], v[32:33], v[202:203] op_sel_hi:[1,0]
	v_pk_mul_f32 v[30:31], v[30:31], v[202:203] op_sel_hi:[1,0]
	v_pk_mul_f32 v[28:29], v[28:29], v[202:203] op_sel_hi:[1,0]
	v_pk_mul_f32 v[26:27], v[26:27], v[202:203] op_sel_hi:[1,0]
	v_pk_mul_f32 v[24:25], v[24:25], v[202:203] op_sel_hi:[1,0]
	v_pk_mul_f32 v[22:23], v[22:23], v[202:203] op_sel_hi:[1,0]
	v_pk_mul_f32 v[20:21], v[20:21], v[202:203] op_sel_hi:[1,0]
	v_pk_mul_f32 v[18:19], v[18:19], v[202:203] op_sel_hi:[1,0]
	v_pk_mul_f32 v[16:17], v[16:17], v[202:203] op_sel_hi:[1,0]
	v_pk_mul_f32 v[14:15], v[14:15], v[202:203] op_sel_hi:[1,0]
	v_pk_mul_f32 v[12:13], v[12:13], v[202:203] op_sel_hi:[1,0]
	v_pk_mul_f32 v[10:11], v[10:11], v[202:203] op_sel_hi:[1,0]
	v_pk_mul_f32 v[8:9], v[8:9], v[202:203] op_sel_hi:[1,0]
	v_pk_mul_f32 v[6:7], v[6:7], v[202:203] op_sel_hi:[1,0]
	v_pk_mul_f32 v[4:5], v[4:5], v[202:203] op_sel_hi:[1,0]
	v_pk_mul_f32 v[2:3], v[2:3], v[202:203] op_sel_hi:[1,0]

.LBB0_71:
	s_andn2_saveexec_b64 s[0:1], s[0:1]
	s_cbranch_execz .LBB0_78
	s_cmp_eq_u32 s44, 3
	s_cbranch_scc1 .LBB0_76
	v_max3_f32 v174, v231, v66, v82
	s_nop 0
	v_max3_f32 v174, v174, v67, v83
	s_nop 0
	v_max3_f32 v174, v174, v68, v84
	s_nop 0
	v_max3_f32 v174, v174, v69, v85
	s_nop 0
	v_max3_f32 v174, v174, v70, v86
	s_nop 0
	v_max3_f32 v174, v174, v71, v87
	s_nop 0
	v_max3_f32 v174, v174, v72, v88
	s_nop 0
	v_max3_f32 v174, v174, v73, v89
	s_nop 0
	v_max3_f32 v174, v174, v74, v90
	s_nop 0
	v_max3_f32 v174, v174, v75, v91
	s_nop 0
	v_max3_f32 v174, v174, v76, v92
	s_nop 0
	v_max3_f32 v174, v174, v77, v93
	s_nop 0
	v_max3_f32 v174, v174, v78, v94
	s_nop 0
	v_max3_f32 v174, v174, v79, v95
	s_nop 0
	v_max3_f32 v174, v174, v80, v96
	s_nop 0
	v_max3_f32 v174, v174, v81, v97
	s_nop 0
	v_mov_b32_e32 v175, v174
	s_nop 1
	v_permlane32_swap_b32_e32 v174, v175
	v_max_f32_e32 v174, v174, v175
	v_add_f32_e32 v175, 0x41000000, v195
	v_cmp_gt_f32_e32 vcc, v174, v175
	v_max_f32_e32 v174, v195, v174
	s_nop 0
	v_cndmask_b32_e32 v215, v195, v174, vcc
	v_cmp_neq_f32_e32 vcc, s59, v215
	s_nop 1
	v_cndmask_b32_e32 v216, 0, v215, vcc
	v_sub_f32_e32 v174, v195, v216
	v_exp_f32_e32 v202, v174
	s_nop 0
	v_cmp_eq_f32_e32 vcc, 1.0, v202
	s_cmp_eq_u64 vcc, exec
	s_cbranch_scc1 .LBB0_75
	v_pk_mul_f32 v[64:65], v[64:65], v[202:203] op_sel_hi:[1,0]
	v_pk_mul_f32 v[62:63], v[62:63], v[202:203] op_sel_hi:[1,0]
	v_pk_mul_f32 v[60:61], v[60:61], v[202:203] op_sel_hi:[1,0]
	v_pk_mul_f32 v[58:59], v[58:59], v[202:203] op_sel_hi:[1,0]
	v_pk_mul_f32 v[56:57], v[56:57], v[202:203] op_sel_hi:[1,0]
	v_pk_mul_f32 v[54:55], v[54:55], v[202:203] op_sel_hi:[1,0]
	v_pk_mul_f32 v[52:53], v[52:53], v[202:203] op_sel_hi:[1,0]
	v_pk_mul_f32 v[50:51], v[50:51], v[202:203] op_sel_hi:[1,0]
	v_pk_mul_f32 v[48:49], v[48:49], v[202:203] op_sel_hi:[1,0]
	v_pk_mul_f32 v[46:47], v[46:47], v[202:203] op_sel_hi:[1,0]
	v_pk_mul_f32 v[44:45], v[44:45], v[202:203] op_sel_hi:[1,0]
	v_pk_mul_f32 v[42:43], v[42:43], v[202:203] op_sel_hi:[1,0]
	v_pk_mul_f32 v[40:41], v[40:41], v[202:203] op_sel_hi:[1,0]
	v_pk_mul_f32 v[38:39], v[38:39], v[202:203] op_sel_hi:[1,0]
	v_pk_mul_f32 v[36:37], v[36:37], v[202:203] op_sel_hi:[1,0]
	v_pk_mul_f32 v[34:35], v[34:35], v[202:203] op_sel_hi:[1,0]
	v_pk_mul_f32 v[32:33], v[32:33], v[202:203] op_sel_hi:[1,0]
	v_pk_mul_f32 v[30:31], v[30:31], v[202:203] op_sel_hi:[1,0]
	v_pk_mul_f32 v[28:29], v[28:29], v[202:203] op_sel_hi:[1,0]
	v_pk_mul_f32 v[26:27], v[26:27], v[202:203] op_sel_hi:[1,0]
	v_pk_mul_f32 v[24:25], v[24:25], v[202:203] op_sel_hi:[1,0]
	v_pk_mul_f32 v[22:23], v[22:23], v[202:203] op_sel_hi:[1,0]
	v_pk_mul_f32 v[20:21], v[20:21], v[202:203] op_sel_hi:[1,0]
	v_pk_mul_f32 v[18:19], v[18:19], v[202:203] op_sel_hi:[1,0]
	v_pk_mul_f32 v[16:17], v[16:17], v[202:203] op_sel_hi:[1,0]
	v_pk_mul_f32 v[14:15], v[14:15], v[202:203] op_sel_hi:[1,0]
	v_pk_mul_f32 v[12:13], v[12:13], v[202:203] op_sel_hi:[1,0]
	v_pk_mul_f32 v[10:11], v[10:11], v[202:203] op_sel_hi:[1,0]
	v_pk_mul_f32 v[8:9], v[8:9], v[202:203] op_sel_hi:[1,0]
	v_pk_mul_f32 v[6:7], v[6:7], v[202:203] op_sel_hi:[1,0]
	v_pk_mul_f32 v[4:5], v[4:5], v[202:203] op_sel_hi:[1,0]
	v_pk_mul_f32 v[2:3], v[2:3], v[202:203] op_sel_hi:[1,0]

.LBB0_90:
	v_not_b32_e32 v66, v218
	v_not_b32_e32 v82, v205
	v_bfe_i32 v83, v66, 0, 1
	v_bfe_i32 v174, v82, 0, 1
	v_bfe_i32 v67, v66, 1, 1
	v_bfe_i32 v175, v82, 1, 1
	v_bfe_i32 v68, v66, 2, 1
	v_bfe_i32 v84, v82, 2, 1
	v_bfe_i32 v69, v66, 3, 1
	v_bfe_i32 v85, v82, 3, 1
	v_bfe_i32 v70, v66, 8, 1
	v_bfe_i32 v86, v82, 8, 1
	v_bfe_i32 v71, v66, 9, 1
	v_bfe_i32 v87, v82, 9, 1
	v_bfe_i32 v72, v66, 10, 1
	v_bfe_i32 v88, v82, 10, 1
	v_bfe_i32 v73, v66, 11, 1
	v_bfe_i32 v89, v82, 11, 1
	v_bfe_i32 v74, v66, 16, 1
	v_bfe_i32 v90, v82, 16, 1
	v_bfe_i32 v75, v66, 17, 1
	v_bfe_i32 v91, v82, 17, 1
	v_bfe_i32 v76, v66, 18, 1
	v_bfe_i32 v92, v82, 18, 1
	v_bfe_i32 v77, v66, 19, 1
	v_bfe_i32 v93, v82, 19, 1
	v_bfe_i32 v78, v66, 24, 1
	v_bfe_i32 v94, v82, 24, 1
	v_bfe_i32 v79, v66, 25, 1
	v_bfe_i32 v95, v82, 25, 1
	v_bfe_i32 v80, v66, 26, 1
	v_bfe_i32 v96, v82, 26, 1
	v_bfe_i32 v66, v66, 27, 1
	v_bfe_i32 v82, v82, 27, 1
	s_nop 0
	v_and_b32_e32 v79, 0xff800000, v79
	v_and_b32_e32 v81, 0xff800000, v66
	v_and_b32_e32 v66, 0xff800000, v83
	v_and_b32_e32 v97, 0xff800000, v82
	v_and_b32_e32 v83, 0xff800000, v175
	v_and_b32_e32 v82, 0xff800000, v174
	ds_read_b128 v[174:177], v217 offset:8704
	ds_read_b128 v[218:221], v217
	ds_read_b128 v[222:225], v217 offset:32
	ds_read_b128 v[226:229], v217 offset:8736
	ds_read_b128 v[232:235], v217 offset:64
	ds_read_b128 v[236:239], v217 offset:8768
	ds_read_b128 v[240:243], v217 offset:96
	ds_read_b128 v[248:251], v217 offset:8800
	v_and_b32_e32 v80, 0xff800000, v80
	v_and_b32_e32 v78, 0xff800000, v78
	v_and_b32_e32 v77, 0xff800000, v77
	v_and_b32_e32 v76, 0xff800000, v76
	v_and_b32_e32 v75, 0xff800000, v75
	v_and_b32_e32 v74, 0xff800000, v74
	v_and_b32_e32 v73, 0xff800000, v73
	v_and_b32_e32 v72, 0xff800000, v72
	v_and_b32_e32 v71, 0xff800000, v71
	v_and_b32_e32 v70, 0xff800000, v70
	v_and_b32_e32 v69, 0xff800000, v69
	v_and_b32_e32 v68, 0xff800000, v68
	v_and_b32_e32 v67, 0xff800000, v67
	v_and_b32_e32 v96, 0xff800000, v96
	v_and_b32_e32 v95, 0xff800000, v95
	v_and_b32_e32 v94, 0xff800000, v94
	v_and_b32_e32 v93, 0xff800000, v93
	v_and_b32_e32 v92, 0xff800000, v92
	v_and_b32_e32 v91, 0xff800000, v91
	v_and_b32_e32 v90, 0xff800000, v90
	v_and_b32_e32 v89, 0xff800000, v89
	v_and_b32_e32 v88, 0xff800000, v88
	v_and_b32_e32 v87, 0xff800000, v87
	v_and_b32_e32 v86, 0xff800000, v86
	v_and_b32_e32 v85, 0xff800000, v85
	v_and_b32_e32 v84, 0xff800000, v84
	s_setprio 1
	s_waitcnt lgkmcnt(6)
	v_mfma_f32_32x32x16_bf16 v[66:81], v[218:221], v[98:101], v[66:81]
	v_mfma_f32_32x32x16_bf16 v[82:97], v[174:177], v[98:101], v[82:97]
	s_waitcnt lgkmcnt(5)
	v_mfma_f32_32x32x16_bf16 v[66:81], v[222:225], v[102:105], v[66:81]
	s_waitcnt lgkmcnt(4)
	v_mfma_f32_32x32x16_bf16 v[82:97], v[226:229], v[102:105], v[82:97]
	s_waitcnt lgkmcnt(3)
	v_mfma_f32_32x32x16_bf16 v[66:81], v[232:235], v[106:109], v[66:81]
	s_waitcnt lgkmcnt(2)
	v_mfma_f32_32x32x16_bf16 v[82:97], v[236:239], v[106:109], v[82:97]
	s_waitcnt lgkmcnt(1)
	v_mfma_f32_32x32x16_bf16 v[66:81], v[240:243], v[110:113], v[66:81]
	s_waitcnt lgkmcnt(0)
	v_mfma_f32_32x32x16_bf16 v[82:97], v[248:251], v[110:113], v[82:97]
	s_setprio 0
	ds_read_b128 v[174:177], v217 offset:128
	ds_read_b128 v[218:221], v217 offset:160
	ds_read_b128 v[222:225], v217 offset:8832
	ds_read_b128 v[226:229], v217 offset:8864
	ds_read_b128 v[232:235], v217 offset:192
	ds_read_b128 v[236:239], v217 offset:224
	ds_read_b128 v[240:243], v217 offset:8896
	ds_read_b128 v[248:251], v217 offset:8928
	s_setprio 1
	s_waitcnt lgkmcnt(7)
	v_mfma_f32_32x32x16_bf16 v[66:81], v[174:177], v[114:117], v[66:81]
	s_waitcnt lgkmcnt(5)
	v_mfma_f32_32x32x16_bf16 v[82:97], v[222:225], v[114:117], v[82:97]
	v_mfma_f32_32x32x16_bf16 v[66:81], v[218:221], v[118:121], v[66:81]
	s_waitcnt lgkmcnt(4)
	v_mfma_f32_32x32x16_bf16 v[82:97], v[226:229], v[118:121], v[82:97]
	s_waitcnt lgkmcnt(3)
	v_mfma_f32_32x32x16_bf16 v[66:81], v[232:235], v[122:125], v[66:81]
	s_waitcnt lgkmcnt(1)
	v_mfma_f32_32x32x16_bf16 v[82:97], v[240:243], v[122:125], v[82:97]
	v_mfma_f32_32x32x16_bf16 v[66:81], v[236:239], v[126:129], v[66:81]
	s_waitcnt lgkmcnt(0)
	v_mfma_f32_32x32x16_bf16 v[82:97], v[248:251], v[126:129], v[82:97]
	s_setprio 0
	v_max3_f32 v174, v231, v66, v82
	s_nop 0
	v_max3_f32 v174, v174, v67, v83
	s_nop 0
	v_max3_f32 v174, v174, v68, v84
	s_nop 0
	v_max3_f32 v174, v174, v69, v85
	s_nop 0
	v_max3_f32 v174, v174, v70, v86
	s_nop 0
	v_max3_f32 v174, v174, v71, v87
	s_nop 0
	v_max3_f32 v174, v174, v72, v88
	s_nop 0
	v_max3_f32 v174, v174, v73, v89
	s_nop 0
	v_max3_f32 v174, v174, v74, v90
	s_nop 0
	v_max3_f32 v174, v174, v75, v91
	s_nop 0
	v_max3_f32 v174, v174, v76, v92
	s_nop 0
	v_max3_f32 v174, v174, v77, v93
	s_nop 0
	v_max3_f32 v174, v174, v78, v94
	s_nop 0
	v_max3_f32 v174, v174, v79, v95
	s_nop 0
	v_max3_f32 v174, v174, v80, v96
	s_nop 0
	v_max3_f32 v174, v174, v81, v97
	s_nop 0
	v_mov_b32_e32 v175, v174
	s_nop 1
	v_permlane32_swap_b32_e32 v174, v175
	v_max_f32_e32 v174, v174, v175
	v_add_f32_e32 v175, 0x41000000, v215
	v_cmp_gt_f32_e32 vcc, v174, v175
	v_max_f32_e32 v174, v215, v174
	s_nop 0
	v_cndmask_b32_e32 v195, v215, v174, vcc
	v_cmp_neq_f32_e32 vcc, s59, v195
	s_nop 1
	v_cndmask_b32_e32 v193, 0, v195, vcc
	v_sub_f32_e32 v174, v215, v193
	v_exp_f32_e32 v204, v174
	s_nop 0
	v_cmp_eq_f32_e32 vcc, 1.0, v204
	s_cmp_eq_u64 vcc, exec
	s_cbranch_scc1 .LBB0_92
	v_pk_mul_f32 v[64:65], v[64:65], v[204:205] op_sel_hi:[1,0]
	v_pk_mul_f32 v[62:63], v[62:63], v[204:205] op_sel_hi:[1,0]
	v_pk_mul_f32 v[60:61], v[60:61], v[204:205] op_sel_hi:[1,0]
	v_pk_mul_f32 v[58:59], v[58:59], v[204:205] op_sel_hi:[1,0]
	v_pk_mul_f32 v[56:57], v[56:57], v[204:205] op_sel_hi:[1,0]
	v_pk_mul_f32 v[54:55], v[54:55], v[204:205] op_sel_hi:[1,0]
	v_pk_mul_f32 v[52:53], v[52:53], v[204:205] op_sel_hi:[1,0]
	v_pk_mul_f32 v[50:51], v[50:51], v[204:205] op_sel_hi:[1,0]
	v_pk_mul_f32 v[48:49], v[48:49], v[204:205] op_sel_hi:[1,0]
	v_pk_mul_f32 v[46:47], v[46:47], v[204:205] op_sel_hi:[1,0]
	v_pk_mul_f32 v[44:45], v[44:45], v[204:205] op_sel_hi:[1,0]
	v_pk_mul_f32 v[42:43], v[42:43], v[204:205] op_sel_hi:[1,0]
	v_pk_mul_f32 v[40:41], v[40:41], v[204:205] op_sel_hi:[1,0]
	v_pk_mul_f32 v[38:39], v[38:39], v[204:205] op_sel_hi:[1,0]
	v_pk_mul_f32 v[36:37], v[36:37], v[204:205] op_sel_hi:[1,0]
	v_pk_mul_f32 v[34:35], v[34:35], v[204:205] op_sel_hi:[1,0]
	v_pk_mul_f32 v[32:33], v[32:33], v[204:205] op_sel_hi:[1,0]
	v_pk_mul_f32 v[30:31], v[30:31], v[204:205] op_sel_hi:[1,0]
	v_pk_mul_f32 v[28:29], v[28:29], v[204:205] op_sel_hi:[1,0]
	v_pk_mul_f32 v[26:27], v[26:27], v[204:205] op_sel_hi:[1,0]
	v_pk_mul_f32 v[24:25], v[24:25], v[204:205] op_sel_hi:[1,0]
	v_pk_mul_f32 v[22:23], v[22:23], v[204:205] op_sel_hi:[1,0]
	v_pk_mul_f32 v[20:21], v[20:21], v[204:205] op_sel_hi:[1,0]
	v_pk_mul_f32 v[18:19], v[18:19], v[204:205] op_sel_hi:[1,0]
	v_pk_mul_f32 v[16:17], v[16:17], v[204:205] op_sel_hi:[1,0]
	v_pk_mul_f32 v[14:15], v[14:15], v[204:205] op_sel_hi:[1,0]
	v_pk_mul_f32 v[12:13], v[12:13], v[204:205] op_sel_hi:[1,0]
	v_pk_mul_f32 v[10:11], v[10:11], v[204:205] op_sel_hi:[1,0]
	v_pk_mul_f32 v[8:9], v[8:9], v[204:205] op_sel_hi:[1,0]
	v_pk_mul_f32 v[6:7], v[6:7], v[204:205] op_sel_hi:[1,0]
	v_pk_mul_f32 v[4:5], v[4:5], v[204:205] op_sel_hi:[1,0]
	v_pk_mul_f32 v[2:3], v[2:3], v[204:205] op_sel_hi:[1,0]

.LBB0_93:
	v_max3_f32 v174, v231, v66, v82
	s_nop 0
	v_max3_f32 v174, v174, v67, v83
	s_nop 0
	v_max3_f32 v174, v174, v68, v84
	s_nop 0
	v_max3_f32 v174, v174, v69, v85
	s_nop 0
	v_max3_f32 v174, v174, v70, v86
	s_nop 0
	v_max3_f32 v174, v174, v71, v87
	s_nop 0
	v_max3_f32 v174, v174, v72, v88
	s_nop 0
	v_max3_f32 v174, v174, v73, v89
	s_nop 0
	v_max3_f32 v174, v174, v74, v90
	s_nop 0
	v_max3_f32 v174, v174, v75, v91
	s_nop 0
	v_max3_f32 v174, v174, v76, v92
	s_nop 0
	v_max3_f32 v174, v174, v77, v93
	s_nop 0
	v_max3_f32 v174, v174, v78, v94
	s_nop 0
	v_max3_f32 v174, v174, v79, v95
	s_nop 0
	v_max3_f32 v174, v174, v80, v96
	s_nop 0
	v_max3_f32 v174, v174, v81, v97
	s_nop 0
	v_mov_b32_e32 v175, v174
	s_nop 1
	v_permlane32_swap_b32_e32 v174, v175
	v_max_f32_e32 v174, v174, v175
	v_add_f32_e32 v175, 0x41000000, v215
	v_cmp_gt_f32_e32 vcc, v174, v175
	v_max_f32_e32 v174, v215, v174
	s_nop 0
	v_cndmask_b32_e32 v195, v215, v174, vcc
	v_cmp_neq_f32_e32 vcc, s59, v195
	s_nop 1
	v_cndmask_b32_e32 v193, 0, v195, vcc
	v_sub_f32_e32 v174, v215, v193
	v_exp_f32_e32 v204, v174
	s_nop 0
	v_cmp_eq_f32_e32 vcc, 1.0, v204
	s_cmp_lg_u64 vcc, exec
	s_cbranch_scc0 .LBB0_95
	v_pk_mul_f32 v[64:65], v[64:65], v[204:205] op_sel_hi:[1,0]
	v_pk_mul_f32 v[62:63], v[62:63], v[204:205] op_sel_hi:[1,0]
	v_pk_mul_f32 v[60:61], v[60:61], v[204:205] op_sel_hi:[1,0]
	v_pk_mul_f32 v[58:59], v[58:59], v[204:205] op_sel_hi:[1,0]
	v_pk_mul_f32 v[56:57], v[56:57], v[204:205] op_sel_hi:[1,0]
	v_pk_mul_f32 v[54:55], v[54:55], v[204:205] op_sel_hi:[1,0]
	v_pk_mul_f32 v[52:53], v[52:53], v[204:205] op_sel_hi:[1,0]
	v_pk_mul_f32 v[50:51], v[50:51], v[204:205] op_sel_hi:[1,0]
	v_pk_mul_f32 v[48:49], v[48:49], v[204:205] op_sel_hi:[1,0]
	v_pk_mul_f32 v[46:47], v[46:47], v[204:205] op_sel_hi:[1,0]
	v_pk_mul_f32 v[44:45], v[44:45], v[204:205] op_sel_hi:[1,0]
	v_pk_mul_f32 v[42:43], v[42:43], v[204:205] op_sel_hi:[1,0]
	v_pk_mul_f32 v[40:41], v[40:41], v[204:205] op_sel_hi:[1,0]
	v_pk_mul_f32 v[38:39], v[38:39], v[204:205] op_sel_hi:[1,0]
	v_pk_mul_f32 v[36:37], v[36:37], v[204:205] op_sel_hi:[1,0]
	v_pk_mul_f32 v[34:35], v[34:35], v[204:205] op_sel_hi:[1,0]
	v_pk_mul_f32 v[32:33], v[32:33], v[204:205] op_sel_hi:[1,0]
	v_pk_mul_f32 v[30:31], v[30:31], v[204:205] op_sel_hi:[1,0]
	v_pk_mul_f32 v[28:29], v[28:29], v[204:205] op_sel_hi:[1,0]
	v_pk_mul_f32 v[26:27], v[26:27], v[204:205] op_sel_hi:[1,0]
	v_pk_mul_f32 v[24:25], v[24:25], v[204:205] op_sel_hi:[1,0]
	v_pk_mul_f32 v[22:23], v[22:23], v[204:205] op_sel_hi:[1,0]
	v_pk_mul_f32 v[20:21], v[20:21], v[204:205] op_sel_hi:[1,0]
	v_pk_mul_f32 v[18:19], v[18:19], v[204:205] op_sel_hi:[1,0]
	v_pk_mul_f32 v[16:17], v[16:17], v[204:205] op_sel_hi:[1,0]
	v_pk_mul_f32 v[14:15], v[14:15], v[204:205] op_sel_hi:[1,0]
	v_pk_mul_f32 v[12:13], v[12:13], v[204:205] op_sel_hi:[1,0]
	v_pk_mul_f32 v[10:11], v[10:11], v[204:205] op_sel_hi:[1,0]
	v_pk_mul_f32 v[8:9], v[8:9], v[204:205] op_sel_hi:[1,0]
	v_pk_mul_f32 v[6:7], v[6:7], v[204:205] op_sel_hi:[1,0]
	v_pk_mul_f32 v[4:5], v[4:5], v[204:205] op_sel_hi:[1,0]
	v_pk_mul_f32 v[2:3], v[2:3], v[204:205] op_sel_hi:[1,0]

.LBB0_96:
	s_and_saveexec_b64 s[0:1], s[4:5]
	s_cbranch_execz .LBB0_57
	v_max3_f32 v98, v231, v66, v82
	s_nop 0
	v_max3_f32 v98, v98, v67, v83
	s_nop 0
	v_max3_f32 v98, v98, v68, v84
	s_nop 0
	v_max3_f32 v98, v98, v69, v85
	s_nop 0
	v_max3_f32 v98, v98, v70, v86
	s_nop 0
	v_max3_f32 v98, v98, v71, v87
	s_nop 0
	v_max3_f32 v98, v98, v72, v88
	s_nop 0
	v_max3_f32 v98, v98, v73, v89
	s_nop 0
	v_max3_f32 v98, v98, v74, v90
	s_nop 0
	v_max3_f32 v98, v98, v75, v91
	s_nop 0
	v_max3_f32 v98, v98, v76, v92
	s_nop 0
	v_max3_f32 v98, v98, v77, v93
	s_nop 0
	v_max3_f32 v98, v98, v78, v94
	s_nop 0
	v_max3_f32 v98, v98, v79, v95
	s_nop 0
	v_max3_f32 v98, v98, v80, v96
	s_nop 0
	v_max3_f32 v98, v98, v81, v97
	s_nop 0
	v_mov_b32_e32 v99, v98
	s_nop 1
	v_permlane32_swap_b32_e32 v98, v99
	v_max_f32_e32 v98, v98, v99
	v_add_f32_e32 v99, 0x41000000, v195
	v_cmp_gt_f32_e32 vcc, v98, v99
	v_max_f32_e32 v98, v195, v98
	s_nop 0
	v_cndmask_b32_e32 v98, v195, v98, vcc
	v_cmp_neq_f32_e32 vcc, s59, v98
	s_nop 1
	v_cndmask_b32_e32 v99, 0, v98, vcc
	v_sub_f32_e32 v98, v195, v99
	v_exp_f32_e32 v98, v98
	s_nop 0
	v_cmp_eq_f32_e32 vcc, 1.0, v98
	s_cmp_lg_u64 vcc, exec
	s_cbranch_scc0 .LBB0_56
	v_pk_mul_f32 v[64:65], v[64:65], v[98:99] op_sel_hi:[1,0]
	v_pk_mul_f32 v[62:63], v[62:63], v[98:99] op_sel_hi:[1,0]
	v_pk_mul_f32 v[60:61], v[60:61], v[98:99] op_sel_hi:[1,0]
	v_pk_mul_f32 v[58:59], v[58:59], v[98:99] op_sel_hi:[1,0]
	v_pk_mul_f32 v[56:57], v[56:57], v[98:99] op_sel_hi:[1,0]
	v_pk_mul_f32 v[54:55], v[54:55], v[98:99] op_sel_hi:[1,0]
	v_pk_mul_f32 v[52:53], v[52:53], v[98:99] op_sel_hi:[1,0]
	v_pk_mul_f32 v[50:51], v[50:51], v[98:99] op_sel_hi:[1,0]
	v_pk_mul_f32 v[48:49], v[48:49], v[98:99] op_sel_hi:[1,0]
	v_pk_mul_f32 v[46:47], v[46:47], v[98:99] op_sel_hi:[1,0]
	v_pk_mul_f32 v[44:45], v[44:45], v[98:99] op_sel_hi:[1,0]
	v_pk_mul_f32 v[42:43], v[42:43], v[98:99] op_sel_hi:[1,0]
	v_pk_mul_f32 v[40:41], v[40:41], v[98:99] op_sel_hi:[1,0]
	v_pk_mul_f32 v[38:39], v[38:39], v[98:99] op_sel_hi:[1,0]
	v_pk_mul_f32 v[36:37], v[36:37], v[98:99] op_sel_hi:[1,0]
	v_pk_mul_f32 v[34:35], v[34:35], v[98:99] op_sel_hi:[1,0]
	v_pk_mul_f32 v[32:33], v[32:33], v[98:99] op_sel_hi:[1,0]
	v_pk_mul_f32 v[30:31], v[30:31], v[98:99] op_sel_hi:[1,0]
	v_pk_mul_f32 v[28:29], v[28:29], v[98:99] op_sel_hi:[1,0]
	v_pk_mul_f32 v[26:27], v[26:27], v[98:99] op_sel_hi:[1,0]
	v_pk_mul_f32 v[24:25], v[24:25], v[98:99] op_sel_hi:[1,0]
	v_pk_mul_f32 v[22:23], v[22:23], v[98:99] op_sel_hi:[1,0]
	v_pk_mul_f32 v[20:21], v[20:21], v[98:99] op_sel_hi:[1,0]
	v_pk_mul_f32 v[18:19], v[18:19], v[98:99] op_sel_hi:[1,0]
	v_pk_mul_f32 v[16:17], v[16:17], v[98:99] op_sel_hi:[1,0]
	v_pk_mul_f32 v[14:15], v[14:15], v[98:99] op_sel_hi:[1,0]
	v_pk_mul_f32 v[12:13], v[12:13], v[98:99] op_sel_hi:[1,0]
	v_pk_mul_f32 v[10:11], v[10:11], v[98:99] op_sel_hi:[1,0]
	v_pk_mul_f32 v[8:9], v[8:9], v[98:99] op_sel_hi:[1,0]
	v_pk_mul_f32 v[6:7], v[6:7], v[98:99] op_sel_hi:[1,0]
	v_pk_mul_f32 v[4:5], v[4:5], v[98:99] op_sel_hi:[1,0]
	v_pk_mul_f32 v[2:3], v[2:3], v[98:99] op_sel_hi:[1,0]
	s_branch .LBB0_56
